# dilated attention: Q fragment loads issued with the staging loads (one wait)
# baseline (speedup 1.0000x reference)
; template <int DQK, int DV, class C>
; DI void flash_item(const C& c, const int lane) {
;     ...
;     const u16* q = c.qrow(r) + 8 * h;
; #pragma unroll
;     for (int s = 0; s < DQK / 16; ++s) qf[s] = *(const bf16x8*)(q + 16 * s);
; __global__ void __launch_bounds__(NTHR) mega(Params p) {
;     ...
;         const int g = it / 1024, rem = it & 1023;
;         const int b = rem >> 8, hd = (rem >> 5) & 7, q8 = rem & 31;
;         const int sh = (g == 0) ? 0 : (g == 1 ? 2 : 4);
;         const int dil = 1 << sh;
;         const int tpc = 256 >> sh;
;         const int qt0 = q8 * 8;
;         const int cr = qt0 / tpc, ti0 = qt0 - cr * tpc, ti = ti0 + wv;
;         const size_t tb = (size_t)b * SEQ + cr;
;         u16* KsL = (u16*)smem;
;         u16* VsL = KsL + 384 * 72;
;         const u16* kgl = Kk + tb * 1536 + g * 512 + hd * 64;
;         const u16* vgl = Vt + ((size_t)((b * 3 + g) * 8 + hd) * 64) * SEQ + (size_t)cr * (SEQ >> sh);
;         const int kp00 = 32 * ti0 - 128;
;         __syncthreads();
; #pragma unroll
;         for (int i = 0; i < 6; ++i) {
;           const int c = tid + NTHR * i;
;           const int prow = c >> 3, ch = c & 7;
;           int kp = kp00 + prow; if (kp < 0) kp = 0;
;           *(uint4*)(KsL + prow * 72 + ch * 8) = *(const uint4*)(kgl + (size_t)kp * dil * 1536 + ch * 8);
;         }
; #pragma unroll
;         for (int i = 0; i < 6; ++i) {
;           const int c = tid + NTHR * i;
;           const int dv = c / 48, ch = c - dv * 48;
;           int kp = kp00 + 8 * ch; if (kp < 0) kp = 0;
;           *(uint4*)(VsL + dv * 392 + ch * 8) = *(const uint4*)(vgl + (size_t)dv * SEQ + kp);
;         }
;         __syncthreads();
.LBB0_3127:
	s_ashr_i32 s6, s12, 31
	s_lshr_b32 s6, s6, 22
	s_add_i32 s6, s12, s6
	s_and_b32 s18, s11, 0xf8
	s_ashr_i32 s8, s6, 10
	s_bfe_u32 s21, s12, 0x20008
	s_bfe_u32 s14, s12, 0x30005
	s_add_i32 s6, s12, 0x3ff
	s_and_b32 s7, s12, 0xfffffc00
	s_cmpk_eq_i32 s7, 0x400
	s_cselect_b32 s7, 2, 4
	s_cmpk_gt_u32 s6, 0x7fe
	s_cselect_b32 s13, s7, 0
	s_lshl_b32 s6, s12, 3
	s_and_b32 s6, s6, 0xf8
	s_sub_i32 s7, 8, s13
	s_lshr_b32 s24, s6, s7
	s_lshl_b32 s19, s24, s7
	s_sub_i32 s17, s6, s19
	s_lshl_b32 s6, s21, 13
	s_or_b32 s15, s24, s6
	s_mul_i32 s9, s15, 0xc00
	s_add_u32 s16, s30, s9
	s_addc_u32 s20, s31, 0
	s_lshl_b32 s6, s8, 9
	s_ashr_i32 s7, s6, 31
	s_lshl_b64 s[6:7], s[6:7], 1
	s_add_u32 s22, s16, s6
	s_addc_u32 s23, s20, s7
	s_lshl_b32 s16, s14, 6
	s_lshl_b32 s20, s14, 7
	s_add_u32 s22, s22, s20
	s_addc_u32 s23, s23, 0
	s_lshl_b32 s25, s17, 5
	s_addk_i32 s25, 0xff80
	v_add_u32_e32 v2, s25, v99
	v_max_i32_e32 v2, 0, v2
	v_mov_b32_e32 v3, v1
	v_lshl_add_u64 v[6:7], s[22:23], 0, v[0:1]
	v_lshlrev_b64 v[2:3], s13, v[2:3]
	v_mad_u64_u32 v[4:5], s[22:23], v2, s69, v[6:7]
	v_mad_u32_u24 v5, v3, s69, v5
	s_barrier
	global_load_dwordx4 v[176:179], v[4:5], off
	v_add_u32_e32 v8, s25, v71
	v_mov_b32_e32 v9, v1
	v_max_i32_e32 v8, 0, v8
	v_lshlrev_b64 v[8:9], s13, v[8:9]
	v_mad_u64_u32 v[10:11], s[22:23], v8, s69, v[6:7]
	v_mad_u32_u24 v11, v9, s69, v11
	v_add_u32_e32 v8, s25, v73
	v_mov_b32_e32 v9, v1
	v_max_i32_e32 v8, 0, v8
	v_lshlrev_b64 v[8:9], s13, v[8:9]
	s_mul_i32 s21, s21, 3
	s_add_i32 s21, s21, s8
	s_lshl_b32 s21, s21, 3
	v_mov_b32_e32 v44, 0
	v_mov_b32_e32 v43, 0xf149f2ca
	v_mov_b32_e32 v115, v114
	v_mov_b32_e32 v116, v112
	v_mov_b32_e32 v117, v111
	v_mov_b32_e32 v18, 0
	v_mov_b32_e32 v19, v44
	v_mov_b32_e32 v20, v44
	v_mov_b32_e32 v21, v44
	v_mov_b32_e32 v22, v44
	v_mov_b32_e32 v23, v44
	v_mov_b32_e32 v24, v44
	v_mov_b32_e32 v25, v44
	v_mov_b32_e32 v26, v44
	v_mov_b32_e32 v27, v44
	v_mov_b32_e32 v28, v44
	v_mov_b32_e32 v29, v44
	v_mov_b32_e32 v30, v44
	v_mov_b32_e32 v31, v44
	v_mov_b32_e32 v32, v44
	v_mov_b32_e32 v33, v44
	v_mov_b32_e32 v12, v44
	v_mov_b32_e32 v13, v44
	v_mov_b32_e32 v14, v44
	v_mov_b32_e32 v15, v44
	v_mov_b32_e32 v16, v44
	v_mov_b32_e32 v17, v44
	global_load_dwordx4 v[180:183], v[10:11], off
	v_mad_u64_u32 v[10:11], s[22:23], v8, s69, v[6:7]
	v_mad_u32_u24 v11, v9, s69, v11
	v_add_u32_e32 v8, s25, v75
	v_mov_b32_e32 v9, v1
	v_max_i32_e32 v8, 0, v8
	v_lshlrev_b64 v[8:9], s13, v[8:9]
	global_load_dwordx4 v[184:187], v[10:11], off
	v_mad_u64_u32 v[10:11], s[22:23], v8, s69, v[6:7]
	v_mad_u32_u24 v11, v9, s69, v11
	v_add_u32_e32 v8, s25, v77
	v_mov_b32_e32 v9, v1
	v_max_i32_e32 v8, 0, v8
	v_lshlrev_b64 v[8:9], s13, v[8:9]
	global_load_dwordx4 v[188:191], v[10:11], off
	v_mad_u64_u32 v[10:11], s[22:23], v8, s69, v[6:7]
	v_mad_u32_u24 v11, v9, s69, v11
	v_add_u32_e32 v8, s25, v79
	v_mov_b32_e32 v9, v1
	v_max_i32_e32 v8, 0, v8
	v_lshlrev_b64 v[8:9], s13, v[8:9]
	v_mad_u64_u32 v[6:7], s[22:23], v8, s69, v[6:7]
	v_mad_u32_u24 v7, v9, s69, v7
	s_sub_i32 s22, 13, s13
	s_lshl_b32 s24, s24, s22
	s_or_b32 s22, s21, s14
	s_ashr_i32 s23, s22, 31
	s_lshl_b64 s[22:23], s[22:23], 20
	s_add_u32 s21, s34, s22
	s_addc_u32 s23, s35, s23
	s_lshl_b32 s22, s24, 1
	s_add_u32 s22, s21, s22
	s_addc_u32 s23, s23, 0
	v_lshl_add_u64 v[8:9], s[22:23], 0, v[82:83]
	s_add_i32 s17, s17, s10
	s_add_u32 s9, s84, s9
	s_addc_u32 s21, s85, 0
	s_add_u32 s6, s9, s6
	s_addc_u32 s7, s21, s7
	s_add_u32 s6, s6, s20
	s_addc_u32 s7, s7, 0
	s_lshl_b32 s17, s17, 5
	s_lshl_b32 s9, 0xc00, s13
	v_or_b32_e32 v94, s17, v97
	v_ashrrev_i32_e32 v95, 31, v94
	global_load_dwordx4 v[192:195], v[10:11], off
	v_mov_b32_e32 v10, v44
	v_mov_b32_e32 v11, v44
	global_load_dwordx4 v[196:199], v[6:7], off
	v_add_u32_e32 v6, s25, v81
	v_max_i32_e32 v6, 0, v6
	v_mov_b32_e32 v7, v1
	v_lshlrev_b32_e32 v6, 1, v6
	v_lshl_add_u64 v[6:7], v[8:9], 0, v[6:7]
	v_lshl_add_u64 v[8:9], s[22:23], 0, v[84:85]
	global_load_dwordx4 v[200:203], v[6:7], off
	v_add_u32_e32 v6, s25, v101
	v_max_i32_e32 v6, 0, v6
	v_mov_b32_e32 v7, v1
	v_lshlrev_b32_e32 v6, 1, v6
	v_lshl_add_u64 v[6:7], v[8:9], 0, v[6:7]
	v_lshl_add_u64 v[8:9], s[22:23], 0, v[86:87]
	global_load_dwordx4 v[204:207], v[6:7], off
	v_add_u32_e32 v6, s25, v103
	v_max_i32_e32 v6, 0, v6
	v_mov_b32_e32 v7, v1
	v_lshlrev_b32_e32 v6, 1, v6
	v_lshl_add_u64 v[6:7], v[8:9], 0, v[6:7]
	v_lshl_add_u64 v[8:9], s[22:23], 0, v[88:89]
	global_load_dwordx4 v[208:211], v[6:7], off
	v_add_u32_e32 v6, s25, v105
	v_max_i32_e32 v6, 0, v6
	v_mov_b32_e32 v7, v1
	v_lshlrev_b32_e32 v6, 1, v6
	v_lshl_add_u64 v[6:7], v[8:9], 0, v[6:7]
	v_lshl_add_u64 v[8:9], s[22:23], 0, v[90:91]
	global_load_dwordx4 v[212:215], v[6:7], off
	v_add_u32_e32 v6, s25, v107
	v_max_i32_e32 v6, 0, v6
	v_mov_b32_e32 v7, v1
	v_lshlrev_b32_e32 v6, 1, v6
	v_lshl_add_u64 v[6:7], v[8:9], 0, v[6:7]
	v_lshl_add_u64 v[8:9], s[22:23], 0, v[92:93]
	global_load_dwordx4 v[216:219], v[6:7], off
	v_add_u32_e32 v6, s25, v109
	v_max_i32_e32 v6, 0, v6
	v_mov_b32_e32 v7, v1
	v_lshlrev_b32_e32 v6, 1, v6
	v_lshl_add_u64 v[6:7], v[8:9], 0, v[6:7]
	v_mov_b32_e32 v8, v44
	v_mov_b32_e32 v9, v44
	global_load_dwordx4 v[220:223], v[6:7], off
	v_mov_b64_e32 v[6:7], s[6:7]
	v_mad_i64_i32 v[6:7], s[6:7], s9, v94, v[6:7]
	v_lshl_add_u64 v[6:7], v[66:67], 1, v[6:7]
	s_add_i32 s6, s10, s18
	s_sub_i32 s6, s6, s19
	s_mov_b32 s9, 0
	s_lshl_b32 s18, s6, 5
	global_load_dwordx4 v[50:53], v[6:7], off
	global_load_dwordx4 v[54:57], v[6:7], off offset:32
	global_load_dwordx4 v[58:61], v[6:7], off offset:64
	global_load_dwordx4 v[62:65], v[6:7], off offset:96
	s_waitcnt vmcnt(0)
	ds_write_b128 v70, v[176:179]
	ds_write_b128 v72, v[180:183]
	ds_write_b128 v74, v[184:187]
	ds_write_b128 v76, v[188:191]
	ds_write_b128 v78, v[192:195]
	ds_write_b128 v80, v[196:199]
	ds_write_b128 v100, v[200:203]
	ds_write_b128 v102, v[204:207]
	ds_write_b128 v104, v[208:211]
	ds_write_b128 v106, v[212:215]
	ds_write_b128 v108, v[216:219]
	ds_write_b128 v110, v[220:223]
	s_waitcnt lgkmcnt(0)
	s_barrier
	v_mov_b32_e32 v2, 0
	v_mov_b32_e32 v3, v44
	v_mov_b32_e32 v4, v44
	v_mov_b32_e32 v5, v44
	v_mov_b32_e32 v6, v44
	v_mov_b32_e32 v7, v44
